# v32 + P7 sample-row split-K first/last stagger keyed on blockIdx bit 3 (within-XCD) instead of bit 0
# speedup vs baseline: 1.0294x; 1.0025x over previous
; #define LAS __attribute__((address_space(3)))
; template <int MT, class Epi>
; DI void skinny_unit(LAS unsigned char* lds, const bf16_t* A, const bf16_t* Wt, int K, int cgi, int k0, int row0, const Epi& E, int tid) {
;     const int lane = tid & 63, wid = tid >> 6, fr = lane & 15, fq = lane >> 4;
;     const int c0 = cgi * 32;
;     constexpr int NMT = 2 * MT;
;     const bf16_t* pa = A + (size_t)(row0 + fr) * K + k0 + wid * 256 + 8 * fq;
;     const bf16_t* pb = Wt + (size_t)(c0 + fr) * K + k0 + wid * 256 + 8 * fq;
;     const size_t rs = (size_t)16 * K;
; __global__ void __launch_bounds__(512, 2) fwd_kernel(Args a) {
;     ...
;     if (IN(7)) {
;         if (bx & 1) for (int u = bx; u < 4 * (DM / 32); u += G) { const SkSlab SE{SLAB + (size_t)(u & 3) * NS * DM}; skinny_unit<4>(lds, U + (size_t)LP * FF, WDN, FF, u >> 2, (u & 3) * 2048, 0, SE, tid); }
;         pg8::Gemm g{U, WDN, LP, DM, FF}; pg8::StaticOrder S; S.init(LP, DM, G, bx, WGM_DN);
;         pg8::EpiDown E{out + O_Y, XG, RSTD2};
;         pg8::gemm_phase<pg8::EpiDown, pg8::StaticOrder, true, true>(lds, g, S, E);
;         if (!(bx & 1)) for (int u = bx; u < 4 * (DM / 32); u += G) { const SkSlab SE{SLAB + (size_t)(u & 3) * NS * DM}; skinny_unit<4>(lds, U + (size_t)LP * FF, WDN, FF, u >> 2, (u & 3) * 2048, 0, SE, tid); }
.LBB0_693:
	s_cmp_lt_i32 s62, 8
	s_cselect_b64 s[2:3], -1, 0
	s_add_u32 s4, s60, 0xa300000
	s_addc_u32 s5, s61, 0
	s_and_b64 s[6:7], s[2:3], s[0:1]
	s_andn2_b64 vcc, exec, s[6:7]
	s_cbranch_vccnz .LBB0_727
	s_bfe_u32 s0, s92, 0x10003
	s_cmp_eq_u32 s0, 0
	s_cselect_b64 s[8:9], -1, 0
	s_cmp_eq_u32 s0, 1
	s_cselect_b64 s[2:3], -1, 0
	s_cmpk_lt_i32 s92, 0x100
	s_cselect_b64 s[10:11], -1, 0
	s_and_b64 s[2:3], s[10:11], s[2:3]
	v_bfe_u32 v141, v253, 4, 2
	s_mov_b32 s1, 0
	s_and_b64 vcc, exec, s[2:3]
	v_and_b32_e32 v28, 15, v253
	v_lshlrev_b32_e32 v128, 3, v141
	v_lshlrev_b32_e32 v130, 4, v141
	v_lshrrev_b32_e32 v29, 2, v253
	v_lshlrev_b32_e32 v154, 3, v253
	s_cbranch_vccz .LBB0_698
	s_waitcnt lgkmcnt(0)
	s_mov_b64 exec, -1
	v_and_b32_e32 v70, 15, v253
	v_bfe_u32 v71, v253, 4, 2
	v_lshrrev_b32_e32 v72, 6, v253
	v_mul_u32_u24_e32 v64, 0x4000, v70
	v_lshl_add_u32 v64, v72, 9, v64
	v_lshl_add_u32 v64, v71, 4, v64
	v_readfirstlane_b32 s1, v72
	v_and_b32_e32 v69, 63, v253
	v_lshlrev_b32_e32 v69, 4, v69
	v_mul_u32_u24_e32 v65, 0x4000, v72
	v_lshl_add_u32 v65, v71, 9, v65
	v_lshl_add_u32 v65, v70, 2, v65
	v_lshrrev_b32_e32 v73, 2, v253
	v_and_b32_e32 v74, 3, v253
	v_lshlrev_b32_e32 v66, 7, v73
	v_lshl_add_u32 v66, v74, 5, v66
	v_add_u32_e32 v67, 0x10000, v66
	v_lshlrev_b32_e32 v68, 13, v73
	v_lshl_add_u32 v68, v74, 5, v68
	s_add_u32 s2, s60, 0x12400000
	s_addc_u32 s3, s61, 0
	s_add_u32 s10, s60, 0x3f00000
	s_addc_u32 s11, s61, 0
	s_lshl_b32 s1, s1, 16
	s_add_u32 s2, s2, s1
	s_addc_u32 s3, s3, 0
	s_mov_b32 s0, s92
